# v30 + HGRN chunk MFMA block: deep LDS read-ahead (rotating register pool)
# speedup vs baseline: 1.0080x; 1.0080x over previous
.LBB0_679:
	v_mul_f32_e32 v0, 0x3fb8aa3b, v0
	v_exp_f32_e32 v14, v0
	v_mul_f32_e32 v0, 0x3fb8aa3b, v2
	v_exp_f32_e32 v12, v0
	v_mul_f32_e32 v0, 0x3fb8aa3b, v4
	v_exp_f32_e32 v10, v0
	v_mul_f32_e32 v0, 0x3fb8aa3b, v6
	v_exp_f32_e32 v8, v0
	v_mul_f32_e32 v0, 0x3fb8aa3b, v16
	v_exp_f32_e32 v6, v0
	v_mul_f32_e32 v0, 0x3fb8aa3b, v78
	v_exp_f32_e32 v4, v0
	v_mul_f32_e32 v0, 0x3fb8aa3b, v79
	v_lshl_add_u64 v[78:79], s[50:51], 0, v[140:141]
	s_mov_b64 s[6:7], 0x14711c00
	v_exp_f32_e32 v2, v0
	v_mul_f32_e32 v0, 0x3fb8aa3b, v80
	v_lshl_add_u64 v[80:81], v[78:79], 0, s[6:7]
	s_mov_b32 s6, 0x14711000
	v_add_co_u32_e32 v78, vcc, s6, v78
	v_pk_mul_f32 v[48:49], v[14:15], v[48:49] op_sel_hi:[0,1]
	s_nop 0
	v_addc_co_u32_e32 v79, vcc, 0, v79, vcc
	global_load_dwordx4 v[82:85], v[78:79], off offset:3072
	s_nop 0
	global_load_dwordx4 v[78:81], v[80:81], off offset:16
	s_waitcnt lgkmcnt(0)
	s_barrier
	v_mul_f32_e64 v46, v14, v46
	v_mul_f32_e64 v47, v14, v47
	v_pk_mul_f32 v[76:77], v[12:13], v[76:77] op_sel_hi:[0,1]
	v_pk_mul_f32 v[74:75], v[12:13], v[74:75] op_sel_hi:[0,1]
	v_mul_f32_e64 v68, v10, v68
	v_mul_f32_e64 v69, v10, v69
	v_pk_mul_f32 v[66:67], v[10:11], v[66:67] op_sel_hi:[0,1]
	v_pk_mul_f32 v[60:61], v[8:9], v[60:61] op_sel_hi:[0,1]
	v_mul_f32_e64 v58, v8, v58
	v_mul_f32_e64 v59, v8, v59
	v_pk_mul_f32 v[56:57], v[6:7], v[56:57] op_sel_hi:[0,1]
	v_pk_mul_f32 v[54:55], v[6:7], v[54:55] op_sel_hi:[0,1]
	v_pk_mul_f32 v[52:53], v[4:5], v[52:53] op_sel_hi:[0,1]
	v_pk_mul_f32 v[50:51], v[4:5], v[50:51] op_sel_hi:[0,1]
	v_pk_mul_f32 v[72:73], v[2:3], v[72:73] op_sel_hi:[0,1]
	v_pk_mul_f32 v[70:71], v[2:3], v[70:71] op_sel_hi:[0,1]
	v_exp_f32_e32 v0, v0
	s_nop 0
	v_add_u32_e32 v2, 0x8c00, v202
	v_pk_mul_f32 v[64:65], v[0:1], v[64:65] op_sel_hi:[0,1]
	v_pk_mul_f32 v[62:63], v[0:1], v[62:63] op_sel_hi:[0,1]
	v_add_u32_e32 v0, 0x8800, v202
	v_and_b32_e32 v4, 64, v177
	v_add_u32_e32 v4, 64, v4
	s_mov_b32 s0, 0x25f91000
	s_add_i32 s5, s5, -1
	s_mov_b64 s[6:7], 0x20000
	v_lshl_add_u64 v[132:133], v[132:133], 0, s[8:9]
	v_lshl_add_u64 v[134:135], v[134:135], 0, s[8:9]
	v_lshl_add_u64 v[136:137], v[136:137], 0, s[8:9]
	v_lshl_add_u64 v[140:141], v[140:141], 0, s[86:87]
	s_cmp_lg_u32 s5, 0
	s_nop 1
	ds_read_b128 v[218:221], v160
	ds_read_b128 v[222:225], v124
	ds_read_b128 v[226:229], v125
	ds_read_b128 v[230:233], v193
	ds_read_b128 v[234:237], v126
	ds_read_b128 v[238:241], v160 offset:64
	ds_read_b128 v[242:245], v124 offset:64
	ds_read_b128 v[246:249], v125 offset:64
	ds_read_b128 v[144:147], v193 offset:64
	s_waitcnt lgkmcnt(7)
	v_mfma_f32_16x16x32_bf16 v[86:89], v[218:221], v[222:225], 0
	ds_read_b128 v[180:183], v126 offset:64
	s_waitcnt lgkmcnt(7)
	v_mfma_f32_16x16x32_bf16 v[90:93], v[218:221], v[226:229], 0
	ds_read_b128 v[222:225], v160 offset:128
	s_waitcnt lgkmcnt(7)
	v_mfma_f32_16x16x32_bf16 v[94:97], v[218:221], v[230:233], 0
	ds_read_b128 v[226:229], v124 offset:128
	s_waitcnt lgkmcnt(7)
	v_mfma_f32_16x16x32_bf16 v[98:101], v[218:221], v[234:237], 0
	ds_read_b128 v[230:233], v125 offset:128
	ds_read_b128 v[218:221], v193 offset:128
	s_waitcnt lgkmcnt(7)
	v_mfma_f32_16x16x32_bf16 v[86:89], v[238:241], v[242:245], v[86:89]
	ds_read_b128 v[234:237], v126 offset:128
	s_waitcnt lgkmcnt(7)
	v_mfma_f32_16x16x32_bf16 v[90:93], v[238:241], v[246:249], v[90:93]
	ds_read_b128 v[242:245], v160 offset:192
	s_waitcnt lgkmcnt(7)
	v_mfma_f32_16x16x32_bf16 v[94:97], v[238:241], v[144:147], v[94:97]
	ds_read_b128 v[246:249], v124 offset:192
	s_waitcnt lgkmcnt(7)
	v_mfma_f32_16x16x32_bf16 v[98:101], v[238:241], v[180:183], v[98:101]
	ds_read_b128 v[144:147], v125 offset:192
	ds_read_b128 v[238:241], v193 offset:192
	s_waitcnt lgkmcnt(7)
	v_mfma_f32_16x16x32_bf16 v[86:89], v[222:225], v[226:229], v[86:89]
	ds_read_b128 v[180:183], v126 offset:192
	s_waitcnt lgkmcnt(7)
	v_mfma_f32_16x16x32_bf16 v[90:93], v[222:225], v[230:233], v[90:93]
	ds_read_b128 v[226:229], v161
	s_waitcnt lgkmcnt(7)
	v_mfma_f32_16x16x32_bf16 v[94:97], v[222:225], v[218:221], v[94:97]
	ds_read_b128 v[230:233], v128 offset:53248
	s_waitcnt lgkmcnt(7)
	v_mfma_f32_16x16x32_bf16 v[98:101], v[222:225], v[234:237], v[98:101]
	ds_read_b128 v[218:221], v127 offset:53248
	ds_read_b128 v[222:225], v129 offset:53248
	s_waitcnt lgkmcnt(7)
	v_mfma_f32_16x16x32_bf16 v[86:89], v[242:245], v[246:249], v[86:89]
	ds_read_b128 v[234:237], v130 offset:53248
	s_waitcnt lgkmcnt(7)
	v_mfma_f32_16x16x32_bf16 v[90:93], v[242:245], v[144:147], v[90:93]
	ds_read_b128 v[246:249], v161 offset:64
	s_waitcnt lgkmcnt(7)
	v_mfma_f32_16x16x32_bf16 v[94:97], v[242:245], v[238:241], v[94:97]
	ds_read_b128 v[144:147], v128 offset:53312
	s_waitcnt lgkmcnt(7)
	v_mfma_f32_16x16x32_bf16 v[98:101], v[242:245], v[180:183], v[98:101]
	ds_read_b128 v[238:241], v127 offset:53312
	ds_read_b128 v[242:245], v129 offset:53312
	s_waitcnt lgkmcnt(7)
	v_mfma_f32_16x16x32_bf16 v[86:89], v[226:229], v[230:233], v[86:89]
	ds_read_b128 v[180:183], v130 offset:53312
	s_waitcnt lgkmcnt(7)
	v_mfma_f32_16x16x32_bf16 v[90:93], v[226:229], v[218:221], v[90:93]
	ds_read_b128 v[230:233], v120 offset:53248
	s_waitcnt lgkmcnt(7)
	v_mfma_f32_16x16x32_bf16 v[94:97], v[226:229], v[222:225], v[94:97]
	ds_read_b128 v[218:221], v120 offset:53312
	s_waitcnt lgkmcnt(7)
	v_mfma_f32_16x16x32_bf16 v[98:101], v[226:229], v[234:237], v[98:101]
	ds_read_b128 v[222:225], v131 offset:34816
	ds_read_b128 v[226:229], v195 offset:34816
	s_waitcnt lgkmcnt(7)
	v_mfma_f32_16x16x32_bf16 v[86:89], v[246:249], v[144:147], v[86:89]
	ds_read_b128 v[234:237], v196 offset:34816
	s_waitcnt lgkmcnt(7)
	v_mfma_f32_16x16x32_bf16 v[90:93], v[246:249], v[238:241], v[90:93]
	ds_read_b128 v[144:147], v197 offset:34816
	s_waitcnt lgkmcnt(7)
	v_mfma_f32_16x16x32_bf16 v[94:97], v[246:249], v[242:245], v[94:97]
	ds_read_b128 v[238:241], v198 offset:34816
	s_waitcnt lgkmcnt(7)
	v_mfma_f32_16x16x32_bf16 v[98:101], v[246:249], v[180:183], v[98:101]
	ds_read_b128 v[242:245], v199 offset:34816
	ds_read_b128 v[246:249], v200 offset:34816
	ds_read_b128 v[180:183], v201 offset:34816
	s_waitcnt lgkmcnt(7)
	v_mfma_f32_16x16x32_bf16 v[46:49], v[230:233], v[222:225], v[46:49]
	ds_read_b128 v[222:225], v131 offset:34880
	s_waitcnt lgkmcnt(7)
	v_mfma_f32_16x16x32_bf16 v[74:77], v[230:233], v[226:229], v[74:77]
	ds_read_b128 v[226:229], v195 offset:34880
	s_waitcnt lgkmcnt(7)
	v_mfma_f32_16x16x32_bf16 v[66:69], v[230:233], v[234:237], v[66:69]
	ds_read_b128 v[234:237], v196 offset:34880
	s_waitcnt lgkmcnt(7)
	v_mfma_f32_16x16x32_bf16 v[58:61], v[230:233], v[144:147], v[58:61]
	ds_read_b128 v[144:147], v197 offset:34880
	s_waitcnt lgkmcnt(7)
	v_mfma_f32_16x16x32_bf16 v[54:57], v[230:233], v[238:241], v[54:57]
	ds_read_b128 v[238:241], v198 offset:34880
	s_waitcnt lgkmcnt(7)
	v_mfma_f32_16x16x32_bf16 v[50:53], v[230:233], v[242:245], v[50:53]
	ds_read_b128 v[242:245], v199 offset:34880
	s_waitcnt lgkmcnt(7)
	v_mfma_f32_16x16x32_bf16 v[70:73], v[230:233], v[246:249], v[70:73]
	ds_read_b128 v[246:249], v200 offset:34880
	s_waitcnt lgkmcnt(7)
	v_mfma_f32_16x16x32_bf16 v[62:65], v[230:233], v[180:183], v[62:65]
	ds_read_b128 v[230:233], v201 offset:34880
	s_waitcnt lgkmcnt(7)
	v_mfma_f32_16x16x32_bf16 v[46:49], v[218:221], v[222:225], v[46:49]
	s_waitcnt lgkmcnt(6)
	v_mfma_f32_16x16x32_bf16 v[74:77], v[218:221], v[226:229], v[74:77]
	s_waitcnt lgkmcnt(5)
	v_mfma_f32_16x16x32_bf16 v[66:69], v[218:221], v[234:237], v[66:69]
	s_waitcnt lgkmcnt(4)
	v_mfma_f32_16x16x32_bf16 v[58:61], v[218:221], v[144:147], v[58:61]
	s_waitcnt lgkmcnt(3)
	v_mfma_f32_16x16x32_bf16 v[54:57], v[218:221], v[238:241], v[54:57]
	s_waitcnt lgkmcnt(2)
	v_mfma_f32_16x16x32_bf16 v[50:53], v[218:221], v[242:245], v[50:53]
	s_waitcnt lgkmcnt(1)
	v_mfma_f32_16x16x32_bf16 v[70:73], v[218:221], v[246:249], v[70:73]
	s_waitcnt lgkmcnt(0)
	v_mfma_f32_16x16x32_bf16 v[62:65], v[218:221], v[230:233], v[62:65]
	s_waitcnt lgkmcnt(0)
	s_barrier
	ds_write2_b32 v0, v86, v90 offset1:16
	ds_write2_b32 v2, v88, v92 offset0:8 offset1:24
	ds_write2_b32 v0, v94, v87 offset0:32 offset1:132
	ds_write2_b32 v0, v91, v95 offset0:148 offset1:164
	ds_write2_b32 v2, v96, v89 offset0:40 offset1:140
	ds_write2_b32 v2, v93, v97 offset0:156 offset1:172
	v_add_u32_e32 v0, 0x8800, v203
	ds_write2_b32 v0, v98, v99 offset1:132
	v_add_u32_e32 v0, 0x8c00, v203
	ds_write2_b32 v0, v100, v101 offset0:8 offset1:140
	s_waitcnt lgkmcnt(0)
	s_barrier
	ds_read_b128 v[98:101], v207 offset:34816
	ds_read_b128 v[90:93], v207 offset:34832
	ds_read_b128 v[94:97], v207 offset:34848
	ds_read_b128 v[86:89], v207 offset:34864
	s_waitcnt lgkmcnt(3)
	v_mov_b32_e32 v220, v99
	s_waitcnt lgkmcnt(2)
	v_mov_b32_e32 v221, v91
	v_mov_b32_e32 v218, v98
	v_mov_b32_e32 v219, v90
	v_pk_mul_f32 v[220:221], v[220:221], v[220:221]
	s_waitcnt lgkmcnt(1)
	v_mov_b32_e32 v222, v95
	v_pk_fma_f32 v[218:219], v[218:219], v[218:219], v[220:221]
	v_mov_b32_e32 v220, v100
	v_mov_b32_e32 v221, v92
	v_pk_fma_f32 v[218:219], v[220:221], v[220:221], v[218:219]
	v_mov_b32_e32 v220, v101
	v_mov_b32_e32 v221, v93
	s_waitcnt lgkmcnt(0)
	v_mov_b32_e32 v223, v87
	v_pk_fma_f32 v[218:219], v[220:221], v[220:221], v[218:219]
	v_mov_b32_e32 v220, v94
	v_mov_b32_e32 v221, v86
	v_pk_mul_f32 v[222:223], v[222:223], v[222:223]
	v_xor_b32_e32 v2, 1, v177
	v_pk_fma_f32 v[220:221], v[220:221], v[220:221], v[222:223]
	v_mov_b32_e32 v222, v96
	v_mov_b32_e32 v223, v88
	v_pk_fma_f32 v[220:221], v[222:223], v[222:223], v[220:221]
	v_mov_b32_e32 v222, v97
	v_mov_b32_e32 v223, v89
	v_pk_fma_f32 v[220:221], v[222:223], v[222:223], v[220:221]
	v_add_f32_e32 v0, v218, v219
	v_cmp_lt_i32_e32 vcc, v2, v4
	v_add_f32_e32 v0, v0, v220
	v_add_f32_e32 v0, v0, v221
	v_cndmask_b32_e32 v2, v177, v2, vcc
	v_lshlrev_b32_e32 v2, 2, v2
	ds_bpermute_b32 v2, v2, v0
	s_waitcnt vmcnt(1)
	v_lshlrev_b32_e32 v218, 16, v82
	s_waitcnt lgkmcnt(0)
	v_add_f32_e32 v0, v0, v2
	v_xor_b32_e32 v2, 2, v177
	v_cmp_lt_i32_e32 vcc, v2, v4
	s_nop 1
	v_cndmask_b32_e32 v2, v177, v2, vcc
	v_lshlrev_b32_e32 v2, 2, v2
	ds_bpermute_b32 v2, v2, v0
	s_waitcnt lgkmcnt(0)
	v_add_f32_e32 v0, v0, v2
	v_xor_b32_e32 v2, 4, v177
	v_cmp_lt_i32_e32 vcc, v2, v4
	s_nop 1
	v_cndmask_b32_e32 v2, v177, v2, vcc
	v_lshlrev_b32_e32 v2, 2, v2
	ds_bpermute_b32 v2, v2, v0
	s_waitcnt lgkmcnt(0)
	v_add_f32_e32 v0, v0, v2
	v_fmamk_f32 v0, v0, 0x3c000000, v143
	v_cmp_gt_f32_e32 vcc, s90, v0
	v_mul_f32_e32 v2, 0x4b800000, v0
	s_nop 0
	v_cndmask_b32_e32 v0, v0, v2, vcc
	v_rsq_f32_e32 v0, v0
	s_nop 0
	v_mul_f32_e32 v2, 0x45800000, v0
	v_cndmask_b32_e32 v0, v0, v2, vcc
	v_mul_f32_e32 v2, 0xbfb8aa3b, v218
	v_exp_f32_e32 v2, v2
	v_mul_f32_e32 v219, v98, v0
	v_and_b32_e32 v98, 0xffff0000, v82
	v_mul_f32_e32 v99, v99, v0
	v_add_f32_e32 v2, 1.0, v2
	v_rcp_f32_e32 v102, v2
	v_mul_f32_e32 v2, 0xbfb8aa3b, v98
	v_exp_f32_e32 v2, v2
	v_mul_f32_e32 v95, v95, v0
	v_pk_mul_f32 v[218:219], v[102:103], v[218:219]
	v_mul_f32_e32 v91, v91, v0
	v_add_f32_e32 v2, 1.0, v2
	v_rcp_f32_e32 v2, v2
	v_mul_f32_e32 v4, v218, v219
	v_mul_f32_e32 v87, v87, v0
	v_pk_mul_f32 v[98:99], v[2:3], v[98:99]
	s_nop 0
	v_mul_f32_e32 v2, v98, v99
	v_mul_f32_e32 v99, v94, v0
	s_waitcnt vmcnt(0)
	v_lshlrev_b32_e32 v98, 16, v78
	v_and_b32_e32 v94, 0xffff0000, v78
	v_cvt_pk_bf16_f32 v82, v4, v2
	v_mul_f32_e32 v2, 0xbfb8aa3b, v98
	v_mul_f32_e32 v4, 0xbfb8aa3b, v94
	v_exp_f32_e32 v2, v2
	v_exp_f32_e32 v4, v4
	v_add_f32_e32 v2, 1.0, v2
	v_add_f32_e32 v4, 1.0, v4
	v_rcp_f32_e32 v110, v2
	v_rcp_f32_e32 v10, v4
	v_pk_mul_f32 v[98:99], v[110:111], v[98:99]
	v_pk_mul_f32 v[94:95], v[10:11], v[94:95]
	v_mul_f32_e32 v2, v98, v99
	v_mul_f32_e32 v4, v94, v95
	v_lshlrev_b32_e32 v94, 16, v83
	v_cvt_pk_bf16_f32 v78, v2, v4
	v_mul_f32_e32 v2, 0xbfb8aa3b, v94
	v_exp_f32_e32 v2, v2
	v_mul_f32_e32 v95, v100, v0
	v_add_f32_e32 v2, 1.0, v2
	v_rcp_f32_e32 v104, v2
	s_nop 0
	v_pk_mul_f32 v[94:95], v[104:105], v[94:95]
	s_nop 0
	v_mul_f32_e32 v2, v94, v95
	v_and_b32_e32 v94, 0xffff0000, v83
	v_mul_f32_e32 v4, 0xbfb8aa3b, v94
	v_exp_f32_e32 v4, v4
	v_mul_f32_e32 v95, v101, v0
	v_add_f32_e32 v4, 1.0, v4
	v_rcp_f32_e32 v4, v4
	s_nop 0
	v_pk_mul_f32 v[94:95], v[4:5], v[94:95]
	s_nop 0
	v_mul_f32_e32 v4, v94, v95
	v_lshlrev_b32_e32 v94, 16, v79
	v_cvt_pk_bf16_f32 v83, v2, v4
	v_mul_f32_e32 v2, 0xbfb8aa3b, v94
	v_exp_f32_e32 v2, v2
	v_mul_f32_e32 v95, v96, v0
	v_add_f32_e32 v2, 1.0, v2
	v_rcp_f32_e32 v112, v2
	s_nop 0
	v_pk_mul_f32 v[94:95], v[112:113], v[94:95]
	s_nop 0
	v_mul_f32_e32 v2, v94, v95
	v_and_b32_e32 v94, 0xffff0000, v79
	v_mul_f32_e32 v4, 0xbfb8aa3b, v94
	v_exp_f32_e32 v4, v4
	v_mul_f32_e32 v95, v97, v0
	v_add_f32_e32 v4, 1.0, v4
	v_rcp_f32_e32 v12, v4
	s_nop 0
	v_pk_mul_f32 v[94:95], v[12:13], v[94:95]
	s_nop 0
	v_mul_f32_e32 v4, v94, v95
	v_mul_f32_e32 v95, v90, v0
	v_lshlrev_b32_e32 v94, 16, v84
	v_and_b32_e32 v90, 0xffff0000, v84
	v_cvt_pk_bf16_f32 v79, v2, v4
	v_mul_f32_e32 v2, 0xbfb8aa3b, v94
	v_mul_f32_e32 v4, 0xbfb8aa3b, v90
	v_exp_f32_e32 v2, v2
	v_exp_f32_e32 v4, v4
	v_add_f32_e32 v2, 1.0, v2
	v_add_f32_e32 v4, 1.0, v4
	v_rcp_f32_e32 v106, v2
	v_rcp_f32_e32 v6, v4
	v_pk_mul_f32 v[94:95], v[106:107], v[94:95]
	v_pk_mul_f32 v[90:91], v[6:7], v[90:91]
	v_mul_f32_e32 v2, v94, v95
	v_mul_f32_e32 v4, v90, v91
	v_mul_f32_e32 v91, v86, v0
	v_lshlrev_b32_e32 v90, 16, v80
	v_and_b32_e32 v86, 0xffff0000, v80
	v_cvt_pk_bf16_f32 v84, v2, v4
	v_mul_f32_e32 v2, 0xbfb8aa3b, v90
	v_mul_f32_e32 v4, 0xbfb8aa3b, v86
	v_exp_f32_e32 v2, v2
	v_exp_f32_e32 v4, v4
	v_mov_b32_e32 v6, v211
	v_add_f32_e32 v2, 1.0, v2
	v_add_f32_e32 v4, 1.0, v4
	v_rcp_f32_e32 v114, v2
	v_rcp_f32_e32 v14, v4
	v_pk_mul_f32 v[90:91], v[114:115], v[90:91]
	v_pk_mul_f32 v[86:87], v[14:15], v[86:87]
	v_mul_f32_e32 v2, v90, v91
	v_mul_f32_e32 v4, v86, v87
	v_lshlrev_b32_e32 v86, 16, v85
	v_cvt_pk_bf16_f32 v80, v2, v4
	v_mul_f32_e32 v2, 0xbfb8aa3b, v86
	v_exp_f32_e32 v2, v2
	v_mul_f32_e32 v87, v92, v0
	v_add_f32_e32 v2, 1.0, v2
	v_rcp_f32_e32 v108, v2
	s_nop 0
	v_pk_mul_f32 v[86:87], v[108:109], v[86:87]
	s_nop 0
	v_mul_f32_e32 v2, v86, v87
	v_and_b32_e32 v86, 0xffff0000, v85
	v_mul_f32_e32 v4, 0xbfb8aa3b, v86
	v_exp_f32_e32 v4, v4
	v_mul_f32_e32 v87, v93, v0
	v_add_f32_e32 v4, 1.0, v4
	v_rcp_f32_e32 v8, v4
	s_nop 0
	v_pk_mul_f32 v[86:87], v[8:9], v[86:87]
	s_nop 0
	v_mul_f32_e32 v4, v86, v87
	v_lshlrev_b32_e32 v86, 16, v81
	v_cvt_pk_bf16_f32 v85, v2, v4
	v_mul_f32_e32 v2, 0xbfb8aa3b, v86
	v_exp_f32_e32 v2, v2
	v_mul_f32_e32 v87, v88, v0
	v_mov_b32_e32 v4, v210
	v_add_f32_e32 v2, 1.0, v2
	v_rcp_f32_e32 v116, v2
	s_nop 0
	v_pk_mul_f32 v[86:87], v[116:117], v[86:87]
	s_nop 0
	v_mul_f32_e32 v2, v86, v87
	v_and_b32_e32 v86, 0xffff0000, v81
	v_mul_f32_e32 v87, v89, v0
	v_mul_f32_e32 v0, 0xbfb8aa3b, v86
	v_exp_f32_e32 v0, v0
	s_nop 0
	v_add_f32_e32 v0, 1.0, v0
	v_rcp_f32_e32 v16, v0
	s_nop 0
	v_pk_mul_f32 v[86:87], v[16:17], v[86:87]
	s_nop 0
	v_mul_f32_e32 v0, v86, v87
	v_lshl_add_u64 v[86:87], s[50:51], 0, v[138:139]
	v_add_co_u32_e32 v86, vcc, s0, v86
	v_cvt_pk_bf16_f32 v81, v2, v0
	v_lshl_add_u64 v[138:139], v[138:139], 0, s[6:7]
	s_nop 0
	v_addc_co_u32_e32 v87, vcc, 0, v87, vcc
	global_store_dwordx4 v[86:87], v[82:85], off
	global_store_dwordx4 v[86:87], v[78:81], off offset:16
	v_mov_b32_e32 v0, v208
	v_mov_b32_e32 v2, v209
	v_mov_b32_e32 v16, v212
	v_mov_b32_e32 v78, v213
	v_mov_b32_e32 v79, v214
	v_mov_b32_e32 v80, v215
	s_cbranch_scc0 .LBB0_682
